# +E11 EpiMix (P4) gate loads in 4 batches of 8 into spare registers, one wait per batch instead of 32 serialized waits
# baseline (speedup 1.0000x reference)
; __device__ __forceinline__ float bf_lo(unsigned w) { return __uint_as_float(w << 16); }
; __device__ __forceinline__ float bf_hi(unsigned w) { return __uint_as_float(w & 0xffff0000u); }
;     __device__ __forceinline__ void operator()(f32x4 (&acc)[2][2][4][2], const pg8::Unit& u, int wr, int wc, int fr, int fq) const {
;         const int row0 = u.pm * 256 + wr * 64 + fr, col0 = u.pn * 256 + wc * 32 + 8 * fq;
; #pragma unroll
;         for (int ai = 0; ai < 2; ++ai)
; #pragma unroll
;             for (int m = 0; m < 4; ++m) { const size_t row = (size_t)(row0 + ai * 128 + m * 16);
; #pragma unroll
;                 for (int bj = 0; bj < 2; ++bj) { const int col = col0 + bj * 128;
;                     const u32x4 gw = *(const u32x4*)(proj + row * NPROJ + PC_MG + u.sub * D + col);
;                     float g[8] = {bf_lo(gw.x), bf_hi(gw.x), bf_lo(gw.y), bf_hi(gw.y), bf_lo(gw.z), bf_hi(gw.z), bf_lo(gw.w), bf_hi(gw.w)};
;                     if (u.sub < 2) { const u32x4 nw = *(const u32x4*)(proj + row * NPROJ + PC_MG + (u.sub + 1) * D + col);
;                         const float n[8] = {bf_lo(nw.x), bf_hi(nw.x), bf_lo(nw.y), bf_hi(nw.y), bf_lo(nw.z), bf_hi(nw.z), bf_lo(nw.w), bf_hi(nw.w)};
; #pragma unroll
;                         for (int k = 0; k < 8; ++k) g[k] *= __builtin_amdgcn_rcpf(fmaxf(n[k], 1e-6f)); }
;                     f32x4 v0 = acc[ai][bj][m][0], v1 = acc[ai][bj][m][1];
;                     v0[0] *= g[0]; v0[1] *= g[1]; v0[2] *= g[2]; v0[3] *= g[3]; v1[0] *= g[4]; v1[1] *= g[5]; v1[2] *= g[6]; v1[3] *= g[7];
;                     if (u.sub < 2) { acc[ai][bj][m][0] = v0; acc[ai][bj][m][1] = v1; }
.LBB0_1594:
	v_lshl_add_u32 v168, s74, 8, v147
	v_ashrrev_i32_e32 v169, 31, v168
	v_lshlrev_b64 v[134:135], 15, v[168:169]
	v_lshl_add_u64 v[134:135], s[62:63], 0, v[134:135]
	s_lshl_b32 s28, s30, 11
	v_lshl_or_b32 v4, s31, 8, v177
	v_lshl_add_u64 v[170:171], v[134:135], 0, s[52:53]
	s_ashr_i32 s29, s28, 31
	v_lshl_add_u64 v[134:135], s[28:29], 1, v[170:171]
	v_ashrrev_i32_e32 v5, 31, v4
	v_lshl_add_u64 v[174:175], v[4:5], 1, v[134:135]
	v_mov_b32_e32 v246, v174
	v_mov_b32_e32 v247, v175
	s_mov_b32 s101, 0
	s_mov_b32 s100, 0x0
	v_lshl_add_u64 v[244:245], v[246:247], 0, s[100:101]
	global_load_dwordx4 v[212:215], v[244:245], off
	global_load_dwordx4 v[216:219], v[244:245], off offset:256
	s_mov_b32 s100, 0x1000
	v_lshl_add_u64 v[244:245], v[246:247], 0, s[100:101]
	global_load_dwordx4 v[228:231], v[244:245], off
	global_load_dwordx4 v[232:235], v[244:245], off offset:256
	s_mov_b32 s100, 0x80000
	v_lshl_add_u64 v[244:245], v[246:247], 0, s[100:101]
	global_load_dwordx4 v[220:223], v[244:245], off
	global_load_dwordx4 v[224:227], v[244:245], off offset:256
	s_mov_b32 s100, 0x81000
	v_lshl_add_u64 v[244:245], v[246:247], 0, s[100:101]
	global_load_dwordx4 v[236:239], v[244:245], off
	global_load_dwordx4 v[240:243], v[244:245], off offset:256
	s_waitcnt vmcnt(0)
	s_cmp_lt_i32 s30, 2
	s_cselect_b64 s[12:13], -1, 0
	s_cmp_gt_i32 s30, 1
	s_cselect_b64 s[30:31], -1, 0
	s_and_b64 vcc, exec, s[30:31]
	v_lshlrev_b32_e32 v134, 16, v212
	v_and_b32_e32 v135, 0xffff0000, v212
	v_lshlrev_b32_e32 v136, 16, v213
	v_and_b32_e32 v137, 0xffff0000, v213
	v_lshlrev_b32_e32 v138, 16, v214
	v_and_b32_e32 v139, 0xffff0000, v214
	v_lshlrev_b32_e32 v140, 16, v215
	v_and_b32_e32 v141, 0xffff0000, v215
	s_cbranch_vccnz .LBB0_1596
	s_add_i32 s14, s28, 0x800
	s_ashr_i32 s15, s14, 31
	v_lshl_add_u64 v[172:173], s[14:15], 1, v[170:171]
	v_lshl_add_u64 v[172:173], v[4:5], 1, v[172:173]
	v_lshlrev_b32_e32 v3, 16, v228
	v_max_f32_e32 v3, v3, v3
	v_and_b32_e32 v173, 0xffff0000, v228
	v_max_f32_e32 v3, 0x358637bd, v3
	v_rcp_f32_e32 v172, v3
	v_max_f32_e32 v3, v173, v173
	v_max_f32_e32 v3, 0x358637bd, v3
	v_rcp_f32_e32 v173, v3
	v_lshlrev_b32_e32 v179, 16, v229
	v_max_f32_e32 v3, v179, v179
	v_and_b32_e32 v180, 0xffff0000, v229
	v_max_f32_e32 v3, 0x358637bd, v3
	v_pk_mul_f32 v[134:135], v[172:173], v[134:135]
	v_rcp_f32_e32 v172, v3
	v_max_f32_e32 v3, v180, v180
	v_max_f32_e32 v3, 0x358637bd, v3
	v_rcp_f32_e32 v173, v3
	v_lshlrev_b32_e32 v181, 16, v230
	v_max_f32_e32 v3, v181, v181
	v_and_b32_e32 v182, 0xffff0000, v230
	v_max_f32_e32 v3, 0x358637bd, v3
	v_pk_mul_f32 v[136:137], v[172:173], v[136:137]
	v_rcp_f32_e32 v172, v3
	v_max_f32_e32 v3, v182, v182
	v_max_f32_e32 v3, 0x358637bd, v3
	v_rcp_f32_e32 v173, v3
	v_lshlrev_b32_e32 v184, 16, v231
	v_max_f32_e32 v3, v184, v184
	v_and_b32_e32 v183, 0xffff0000, v231
	v_max_f32_e32 v3, 0x358637bd, v3
	v_pk_mul_f32 v[138:139], v[172:173], v[138:139]
	v_rcp_f32_e32 v172, v3
	v_max_f32_e32 v3, v183, v183
	v_max_f32_e32 v3, 0x358637bd, v3
	v_rcp_f32_e32 v173, v3
	s_nop 0
	v_pk_mul_f32 v[140:141], v[172:173], v[140:141]

; __device__ __forceinline__ float bf_lo(unsigned w) { return __uint_as_float(w << 16); }
; __device__ __forceinline__ float bf_hi(unsigned w) { return __uint_as_float(w & 0xffff0000u); }
;     __device__ __forceinline__ void operator()(f32x4 (&acc)[2][2][4][2], const pg8::Unit& u, int wr, int wc, int fr, int fq) const {
;     ...
;             for (int m = 0; m < 4; ++m) { const size_t row = (size_t)(row0 + ai * 128 + m * 16);
; #pragma unroll
;                 for (int bj = 0; bj < 2; ++bj) { const int col = col0 + bj * 128;
;                     const u32x4 gw = *(const u32x4*)(proj + row * NPROJ + PC_MG + u.sub * D + col);
;                     float g[8] = {bf_lo(gw.x), bf_hi(gw.x), bf_lo(gw.y), bf_hi(gw.y), bf_lo(gw.z), bf_hi(gw.z), bf_lo(gw.w), bf_hi(gw.w)};
;                     if (u.sub < 2) { const u32x4 nw = *(const u32x4*)(proj + row * NPROJ + PC_MG + (u.sub + 1) * D + col);
;                         const float n[8] = {bf_lo(nw.x), bf_hi(nw.x), bf_lo(nw.y), bf_hi(nw.y), bf_lo(nw.z), bf_hi(nw.z), bf_lo(nw.w), bf_hi(nw.w)};
; #pragma unroll
;                         for (int k = 0; k < 8; ++k) g[k] *= __builtin_amdgcn_rcpf(fmaxf(n[k], 1e-6f)); }
;                     f32x4 v0 = acc[ai][bj][m][0], v1 = acc[ai][bj][m][1];
;                     v0[0] *= g[0]; v0[1] *= g[1]; v0[2] *= g[2]; v0[3] *= g[3]; v1[0] *= g[4]; v1[1] *= g[5]; v1[2] *= g[6]; v1[3] *= g[7];
;                     if (u.sub < 2) { acc[ai][bj][m][0] = v0; acc[ai][bj][m][1] = v1; }
.LBB0_1599:
	v_cndmask_b32_e64 v3, 0, 1, s[12:13]
	v_cmp_ne_u32_e64 s[14:15], 1, v3
	s_andn2_b64 vcc, exec, s[12:13]
	v_lshlrev_b32_e32 v134, 16, v216
	v_and_b32_e32 v135, 0xffff0000, v216
	v_lshlrev_b32_e32 v136, 16, v217
	v_and_b32_e32 v137, 0xffff0000, v217
	v_lshlrev_b32_e32 v138, 16, v218
	v_and_b32_e32 v139, 0xffff0000, v218
	v_lshlrev_b32_e32 v140, 16, v219
	v_and_b32_e32 v141, 0xffff0000, v219
	s_cbranch_vccnz .LBB0_1601
	s_add_i32 s12, s28, 0x800
	s_ashr_i32 s13, s12, 31
	v_lshl_add_u64 v[170:171], s[12:13], 1, v[170:171]
	v_lshl_add_u64 v[170:171], v[4:5], 1, v[170:171]
	v_lshlrev_b32_e32 v3, 16, v232
	v_max_f32_e32 v3, v3, v3
	v_and_b32_e32 v169, 0xffff0000, v232
	v_max_f32_e32 v3, 0x358637bd, v3
	v_rcp_f32_e32 v170, v3
	v_max_f32_e32 v3, v169, v169
	v_max_f32_e32 v3, 0x358637bd, v3
	v_rcp_f32_e32 v171, v3
	v_lshlrev_b32_e32 v174, 16, v233
	v_max_f32_e32 v3, v174, v174
	v_and_b32_e32 v175, 0xffff0000, v233
	v_max_f32_e32 v3, 0x358637bd, v3
	v_pk_mul_f32 v[134:135], v[170:171], v[134:135]
	v_rcp_f32_e32 v170, v3
	v_max_f32_e32 v3, v175, v175
	v_max_f32_e32 v3, 0x358637bd, v3
	v_rcp_f32_e32 v171, v3
	v_lshlrev_b32_e32 v179, 16, v234
	v_max_f32_e32 v3, v179, v179
	v_and_b32_e32 v180, 0xffff0000, v234
	v_max_f32_e32 v3, 0x358637bd, v3
	v_pk_mul_f32 v[136:137], v[170:171], v[136:137]
	v_rcp_f32_e32 v170, v3
	v_max_f32_e32 v3, v180, v180
	v_max_f32_e32 v3, 0x358637bd, v3
	v_rcp_f32_e32 v171, v3
	v_lshlrev_b32_e32 v181, 16, v235
	v_max_f32_e32 v3, v181, v181
	v_and_b32_e32 v182, 0xffff0000, v235
	v_max_f32_e32 v3, 0x358637bd, v3
	v_pk_mul_f32 v[138:139], v[170:171], v[138:139]
	v_rcp_f32_e32 v170, v3
	v_max_f32_e32 v3, v182, v182
	v_max_f32_e32 v3, 0x358637bd, v3
	v_rcp_f32_e32 v171, v3
	s_nop 0
	v_pk_mul_f32 v[140:141], v[170:171], v[140:141]

; __device__ __forceinline__ float bf_lo(unsigned w) { return __uint_as_float(w << 16); }
; __device__ __forceinline__ float bf_hi(unsigned w) { return __uint_as_float(w & 0xffff0000u); }
;     __device__ __forceinline__ void operator()(f32x4 (&acc)[2][2][4][2], const pg8::Unit& u, int wr, int wc, int fr, int fq) const {
;     ...
;             for (int m = 0; m < 4; ++m) { const size_t row = (size_t)(row0 + ai * 128 + m * 16);
; #pragma unroll
;                 for (int bj = 0; bj < 2; ++bj) { const int col = col0 + bj * 128;
;                     const u32x4 gw = *(const u32x4*)(proj + row * NPROJ + PC_MG + u.sub * D + col);
;                     float g[8] = {bf_lo(gw.x), bf_hi(gw.x), bf_lo(gw.y), bf_hi(gw.y), bf_lo(gw.z), bf_hi(gw.z), bf_lo(gw.w), bf_hi(gw.w)};
;                     if (u.sub < 2) { const u32x4 nw = *(const u32x4*)(proj + row * NPROJ + PC_MG + (u.sub + 1) * D + col);
;                         const float n[8] = {bf_lo(nw.x), bf_hi(nw.x), bf_lo(nw.y), bf_hi(nw.y), bf_lo(nw.z), bf_hi(nw.z), bf_lo(nw.w), bf_hi(nw.w)};
; #pragma unroll
;                         for (int k = 0; k < 8; ++k) g[k] *= __builtin_amdgcn_rcpf(fmaxf(n[k], 1e-6f)); }
;                     f32x4 v0 = acc[ai][bj][m][0], v1 = acc[ai][bj][m][1];
;                     v0[0] *= g[0]; v0[1] *= g[1]; v0[2] *= g[2]; v0[3] *= g[3]; v1[0] *= g[4]; v1[1] *= g[5]; v1[2] *= g[6]; v1[3] *= g[7];
;                     if (u.sub < 2) { acc[ai][bj][m][0] = v0; acc[ai][bj][m][1] = v1; }
.LBB0_1604:
	s_nop 0
	v_or_b32_e32 v134, 16, v168
	v_ashrrev_i32_e32 v135, 31, v134
	v_lshlrev_b64 v[136:137], 15, v[134:135]
	v_lshl_add_u64 v[136:137], s[62:63], 0, v[136:137]
	v_lshl_add_u64 v[170:171], v[136:137], 0, s[52:53]
	v_lshl_add_u64 v[136:137], s[28:29], 1, v[170:171]
	v_lshl_add_u64 v[174:175], v[4:5], 1, v[136:137]
	s_andn2_b64 vcc, exec, s[30:31]
	s_and_b64 vcc, exec, s[14:15]
	v_lshlrev_b32_e32 v172, 16, v220
	v_and_b32_e32 v173, 0xffff0000, v220
	v_lshlrev_b32_e32 v136, 16, v221
	v_and_b32_e32 v137, 0xffff0000, v221
	v_lshlrev_b32_e32 v138, 16, v222
	v_and_b32_e32 v139, 0xffff0000, v222
	v_lshlrev_b32_e32 v140, 16, v223
	v_and_b32_e32 v141, 0xffff0000, v223
	s_cbranch_vccnz .LBB0_1606
	s_add_i32 s30, s28, 0x800
	s_ashr_i32 s31, s30, 31
	v_lshl_add_u64 v[180:181], s[30:31], 1, v[170:171]
	v_lshl_add_u64 v[180:181], v[4:5], 1, v[180:181]
	v_lshlrev_b32_e32 v3, 16, v236
	v_max_f32_e32 v3, v3, v3
	v_and_b32_e32 v169, 0xffff0000, v236
	v_max_f32_e32 v3, 0x358637bd, v3
	v_rcp_f32_e32 v180, v3
	v_max_f32_e32 v3, v169, v169
	v_max_f32_e32 v3, 0x358637bd, v3
	v_lshlrev_b32_e32 v179, 16, v237
	v_and_b32_e32 v184, 0xffff0000, v237
	v_rcp_f32_e32 v181, v3
	v_max_f32_e32 v3, v179, v179
	v_max_f32_e32 v3, 0x358637bd, v3
	v_lshlrev_b32_e32 v185, 16, v238
	v_pk_mul_f32 v[172:173], v[180:181], v[172:173]
	v_rcp_f32_e32 v180, v3
	v_max_f32_e32 v3, v184, v184
	v_max_f32_e32 v3, 0x358637bd, v3
	v_rcp_f32_e32 v181, v3
	v_max_f32_e32 v3, v185, v185
	v_and_b32_e32 v182, 0xffff0000, v238
	v_max_f32_e32 v3, 0x358637bd, v3
	v_pk_mul_f32 v[136:137], v[180:181], v[136:137]
	v_rcp_f32_e32 v180, v3
	v_max_f32_e32 v3, v182, v182
	v_max_f32_e32 v3, 0x358637bd, v3
	v_rcp_f32_e32 v181, v3
	v_lshlrev_b32_e32 v186, 16, v239
	v_max_f32_e32 v3, v186, v186
	v_and_b32_e32 v183, 0xffff0000, v239
	v_max_f32_e32 v3, 0x358637bd, v3
	v_pk_mul_f32 v[138:139], v[180:181], v[138:139]
	v_rcp_f32_e32 v180, v3
	v_max_f32_e32 v3, v183, v183
	v_max_f32_e32 v3, 0x358637bd, v3
	v_rcp_f32_e32 v181, v3
	s_nop 0
	v_pk_mul_f32 v[140:141], v[180:181], v[140:141]

; __device__ __forceinline__ float bf_lo(unsigned w) { return __uint_as_float(w << 16); }
; __device__ __forceinline__ float bf_hi(unsigned w) { return __uint_as_float(w & 0xffff0000u); }
;     __device__ __forceinline__ void operator()(f32x4 (&acc)[2][2][4][2], const pg8::Unit& u, int wr, int wc, int fr, int fq) const {
;     ...
;             for (int m = 0; m < 4; ++m) { const size_t row = (size_t)(row0 + ai * 128 + m * 16);
; #pragma unroll
;                 for (int bj = 0; bj < 2; ++bj) { const int col = col0 + bj * 128;
;                     const u32x4 gw = *(const u32x4*)(proj + row * NPROJ + PC_MG + u.sub * D + col);
;                     float g[8] = {bf_lo(gw.x), bf_hi(gw.x), bf_lo(gw.y), bf_hi(gw.y), bf_lo(gw.z), bf_hi(gw.z), bf_lo(gw.w), bf_hi(gw.w)};
;                     if (u.sub < 2) { const u32x4 nw = *(const u32x4*)(proj + row * NPROJ + PC_MG + (u.sub + 1) * D + col);
;                         const float n[8] = {bf_lo(nw.x), bf_hi(nw.x), bf_lo(nw.y), bf_hi(nw.y), bf_lo(nw.z), bf_hi(nw.z), bf_lo(nw.w), bf_hi(nw.w)};
; #pragma unroll
;                         for (int k = 0; k < 8; ++k) g[k] *= __builtin_amdgcn_rcpf(fmaxf(n[k], 1e-6f)); }
;                     f32x4 v0 = acc[ai][bj][m][0], v1 = acc[ai][bj][m][1];
;                     v0[0] *= g[0]; v0[1] *= g[1]; v0[2] *= g[2]; v0[3] *= g[3]; v1[0] *= g[4]; v1[1] *= g[5]; v1[2] *= g[6]; v1[3] *= g[7];
;                     if (u.sub < 2) { acc[ai][bj][m][0] = v0; acc[ai][bj][m][1] = v1; }
.LBB0_1609:
	s_andn2_b64 vcc, exec, s[30:31]
	s_and_b64 vcc, exec, s[14:15]
	v_lshlrev_b32_e32 v134, 16, v224
	v_and_b32_e32 v135, 0xffff0000, v224
	v_lshlrev_b32_e32 v136, 16, v225
	v_and_b32_e32 v137, 0xffff0000, v225
	v_lshlrev_b32_e32 v138, 16, v226
	v_and_b32_e32 v139, 0xffff0000, v226
	v_lshlrev_b32_e32 v140, 16, v227
	v_and_b32_e32 v141, 0xffff0000, v227
	s_cbranch_vccnz .LBB0_1611
	s_add_i32 s30, s28, 0x800
	s_ashr_i32 s31, s30, 31
	v_lshl_add_u64 v[170:171], s[30:31], 1, v[170:171]
	v_lshl_add_u64 v[170:171], v[4:5], 1, v[170:171]
	v_lshlrev_b32_e32 v3, 16, v240
	v_max_f32_e32 v3, v3, v3
	v_and_b32_e32 v169, 0xffff0000, v240
	v_max_f32_e32 v3, 0x358637bd, v3
	v_rcp_f32_e32 v170, v3
	v_max_f32_e32 v3, v169, v169
	v_max_f32_e32 v3, 0x358637bd, v3
	v_rcp_f32_e32 v171, v3
	v_lshlrev_b32_e32 v174, 16, v241
	v_max_f32_e32 v3, v174, v174
	v_and_b32_e32 v175, 0xffff0000, v241
	v_max_f32_e32 v3, 0x358637bd, v3
	v_pk_mul_f32 v[134:135], v[170:171], v[134:135]
	v_rcp_f32_e32 v170, v3
	v_max_f32_e32 v3, v175, v175
	v_max_f32_e32 v3, 0x358637bd, v3
	v_rcp_f32_e32 v171, v3
	v_lshlrev_b32_e32 v179, 16, v242
	v_max_f32_e32 v3, v179, v179
	v_and_b32_e32 v180, 0xffff0000, v242
	v_max_f32_e32 v3, 0x358637bd, v3
	v_pk_mul_f32 v[136:137], v[170:171], v[136:137]
	v_rcp_f32_e32 v170, v3
	v_max_f32_e32 v3, v180, v180
	v_max_f32_e32 v3, 0x358637bd, v3
	v_rcp_f32_e32 v171, v3
	v_lshlrev_b32_e32 v181, 16, v243
	v_max_f32_e32 v3, v181, v181
	v_and_b32_e32 v182, 0xffff0000, v243
	v_max_f32_e32 v3, 0x358637bd, v3
	v_pk_mul_f32 v[138:139], v[170:171], v[138:139]
	v_rcp_f32_e32 v170, v3
	v_max_f32_e32 v3, v182, v182
	v_max_f32_e32 v3, 0x358637bd, v3
	v_rcp_f32_e32 v171, v3
	s_nop 0
	v_pk_mul_f32 v[140:141], v[170:171], v[140:141]

; __device__ __forceinline__ float bf_lo(unsigned w) { return __uint_as_float(w << 16); }
; __device__ __forceinline__ float bf_hi(unsigned w) { return __uint_as_float(w & 0xffff0000u); }
;     __device__ __forceinline__ void operator()(f32x4 (&acc)[2][2][4][2], const pg8::Unit& u, int wr, int wc, int fr, int fq) const {
;     ...
;             for (int m = 0; m < 4; ++m) { const size_t row = (size_t)(row0 + ai * 128 + m * 16);
; #pragma unroll
;                 for (int bj = 0; bj < 2; ++bj) { const int col = col0 + bj * 128;
;                     const u32x4 gw = *(const u32x4*)(proj + row * NPROJ + PC_MG + u.sub * D + col);
;                     float g[8] = {bf_lo(gw.x), bf_hi(gw.x), bf_lo(gw.y), bf_hi(gw.y), bf_lo(gw.z), bf_hi(gw.z), bf_lo(gw.w), bf_hi(gw.w)};
;                     if (u.sub < 2) { const u32x4 nw = *(const u32x4*)(proj + row * NPROJ + PC_MG + (u.sub + 1) * D + col);
;                         const float n[8] = {bf_lo(nw.x), bf_hi(nw.x), bf_lo(nw.y), bf_hi(nw.y), bf_lo(nw.z), bf_hi(nw.z), bf_lo(nw.w), bf_hi(nw.w)};
; #pragma unroll
;                         for (int k = 0; k < 8; ++k) g[k] *= __builtin_amdgcn_rcpf(fmaxf(n[k], 1e-6f)); }
;                     f32x4 v0 = acc[ai][bj][m][0], v1 = acc[ai][bj][m][1];
;                     v0[0] *= g[0]; v0[1] *= g[1]; v0[2] *= g[2]; v0[3] *= g[3]; v1[0] *= g[4]; v1[1] *= g[5]; v1[2] *= g[6]; v1[3] *= g[7];
;                     if (u.sub < 2) { acc[ai][bj][m][0] = v0; acc[ai][bj][m][1] = v1; }
.LBB0_1614:
	s_nop 0
	v_or_b32_e32 v134, 32, v168
	v_ashrrev_i32_e32 v135, 31, v134
	v_lshlrev_b64 v[136:137], 15, v[134:135]
	v_lshl_add_u64 v[136:137], s[62:63], 0, v[136:137]
	v_lshl_add_u64 v[170:171], v[136:137], 0, s[52:53]
	v_lshl_add_u64 v[136:137], s[28:29], 1, v[170:171]
	v_lshl_add_u64 v[174:175], v[4:5], 1, v[136:137]
	s_mov_b32 s101, 0
	s_mov_b32 s100, 0x100000
	v_lshl_add_u64 v[244:245], v[246:247], 0, s[100:101]
	global_load_dwordx4 v[212:215], v[244:245], off
	global_load_dwordx4 v[216:219], v[244:245], off offset:256
	s_mov_b32 s100, 0x101000
	v_lshl_add_u64 v[244:245], v[246:247], 0, s[100:101]
	global_load_dwordx4 v[228:231], v[244:245], off
	global_load_dwordx4 v[232:235], v[244:245], off offset:256
	s_mov_b32 s100, 0x180000
	v_lshl_add_u64 v[244:245], v[246:247], 0, s[100:101]
	global_load_dwordx4 v[220:223], v[244:245], off
	global_load_dwordx4 v[224:227], v[244:245], off offset:256
	s_mov_b32 s100, 0x181000
	v_lshl_add_u64 v[244:245], v[246:247], 0, s[100:101]
	global_load_dwordx4 v[236:239], v[244:245], off
	global_load_dwordx4 v[240:243], v[244:245], off offset:256
	s_waitcnt vmcnt(0)
	s_andn2_b64 vcc, exec, s[30:31]
	s_and_b64 vcc, exec, s[14:15]
	v_lshlrev_b32_e32 v172, 16, v212
	v_and_b32_e32 v173, 0xffff0000, v212
	v_lshlrev_b32_e32 v136, 16, v213
	v_and_b32_e32 v137, 0xffff0000, v213
	v_lshlrev_b32_e32 v138, 16, v214
	v_and_b32_e32 v139, 0xffff0000, v214
	v_lshlrev_b32_e32 v140, 16, v215
	v_and_b32_e32 v141, 0xffff0000, v215
	s_cbranch_vccnz .LBB0_1616
	s_add_i32 s30, s28, 0x800
	s_ashr_i32 s31, s30, 31
	v_lshl_add_u64 v[180:181], s[30:31], 1, v[170:171]
	v_lshl_add_u64 v[180:181], v[4:5], 1, v[180:181]
	v_lshlrev_b32_e32 v3, 16, v228
	v_max_f32_e32 v3, v3, v3
	v_and_b32_e32 v169, 0xffff0000, v228
	v_max_f32_e32 v3, 0x358637bd, v3
	v_rcp_f32_e32 v180, v3
	v_max_f32_e32 v3, v169, v169
	v_max_f32_e32 v3, 0x358637bd, v3
	v_lshlrev_b32_e32 v179, 16, v229
	v_and_b32_e32 v184, 0xffff0000, v229
	v_rcp_f32_e32 v181, v3
	v_max_f32_e32 v3, v179, v179
	v_max_f32_e32 v3, 0x358637bd, v3
	v_lshlrev_b32_e32 v185, 16, v230
	v_pk_mul_f32 v[172:173], v[180:181], v[172:173]
	v_rcp_f32_e32 v180, v3
	v_max_f32_e32 v3, v184, v184
	v_max_f32_e32 v3, 0x358637bd, v3
	v_rcp_f32_e32 v181, v3
	v_max_f32_e32 v3, v185, v185
	v_and_b32_e32 v182, 0xffff0000, v230
	v_max_f32_e32 v3, 0x358637bd, v3
	v_pk_mul_f32 v[136:137], v[180:181], v[136:137]
	v_rcp_f32_e32 v180, v3
	v_max_f32_e32 v3, v182, v182
	v_max_f32_e32 v3, 0x358637bd, v3
	v_rcp_f32_e32 v181, v3
	v_lshlrev_b32_e32 v186, 16, v231
	v_max_f32_e32 v3, v186, v186
	v_and_b32_e32 v183, 0xffff0000, v231
	v_max_f32_e32 v3, 0x358637bd, v3
	v_pk_mul_f32 v[138:139], v[180:181], v[138:139]
	v_rcp_f32_e32 v180, v3
	v_max_f32_e32 v3, v183, v183
	v_max_f32_e32 v3, 0x358637bd, v3
	v_rcp_f32_e32 v181, v3
	s_nop 0
	v_pk_mul_f32 v[140:141], v[180:181], v[140:141]

; __device__ __forceinline__ float bf_lo(unsigned w) { return __uint_as_float(w << 16); }
; __device__ __forceinline__ float bf_hi(unsigned w) { return __uint_as_float(w & 0xffff0000u); }
;     __device__ __forceinline__ void operator()(f32x4 (&acc)[2][2][4][2], const pg8::Unit& u, int wr, int wc, int fr, int fq) const {
;     ...
;             for (int m = 0; m < 4; ++m) { const size_t row = (size_t)(row0 + ai * 128 + m * 16);
; #pragma unroll
;                 for (int bj = 0; bj < 2; ++bj) { const int col = col0 + bj * 128;
;                     const u32x4 gw = *(const u32x4*)(proj + row * NPROJ + PC_MG + u.sub * D + col);
;                     float g[8] = {bf_lo(gw.x), bf_hi(gw.x), bf_lo(gw.y), bf_hi(gw.y), bf_lo(gw.z), bf_hi(gw.z), bf_lo(gw.w), bf_hi(gw.w)};
;                     if (u.sub < 2) { const u32x4 nw = *(const u32x4*)(proj + row * NPROJ + PC_MG + (u.sub + 1) * D + col);
;                         const float n[8] = {bf_lo(nw.x), bf_hi(nw.x), bf_lo(nw.y), bf_hi(nw.y), bf_lo(nw.z), bf_hi(nw.z), bf_lo(nw.w), bf_hi(nw.w)};
; #pragma unroll
;                         for (int k = 0; k < 8; ++k) g[k] *= __builtin_amdgcn_rcpf(fmaxf(n[k], 1e-6f)); }
;                     f32x4 v0 = acc[ai][bj][m][0], v1 = acc[ai][bj][m][1];
;                     v0[0] *= g[0]; v0[1] *= g[1]; v0[2] *= g[2]; v0[3] *= g[3]; v1[0] *= g[4]; v1[1] *= g[5]; v1[2] *= g[6]; v1[3] *= g[7];
;                     if (u.sub < 2) { acc[ai][bj][m][0] = v0; acc[ai][bj][m][1] = v1; }
.LBB0_1619:
	s_andn2_b64 vcc, exec, s[30:31]
	s_and_b64 vcc, exec, s[14:15]
	v_lshlrev_b32_e32 v134, 16, v216
	v_and_b32_e32 v135, 0xffff0000, v216
	v_lshlrev_b32_e32 v136, 16, v217
	v_and_b32_e32 v137, 0xffff0000, v217
	v_lshlrev_b32_e32 v138, 16, v218
	v_and_b32_e32 v139, 0xffff0000, v218
	v_lshlrev_b32_e32 v140, 16, v219
	v_and_b32_e32 v141, 0xffff0000, v219
	s_cbranch_vccnz .LBB0_1621
	s_add_i32 s30, s28, 0x800
	s_ashr_i32 s31, s30, 31
	v_lshl_add_u64 v[170:171], s[30:31], 1, v[170:171]
	v_lshl_add_u64 v[170:171], v[4:5], 1, v[170:171]
	v_lshlrev_b32_e32 v3, 16, v232
	v_max_f32_e32 v3, v3, v3
	v_and_b32_e32 v169, 0xffff0000, v232
	v_max_f32_e32 v3, 0x358637bd, v3
	v_rcp_f32_e32 v170, v3
	v_max_f32_e32 v3, v169, v169
	v_max_f32_e32 v3, 0x358637bd, v3
	v_rcp_f32_e32 v171, v3
	v_lshlrev_b32_e32 v174, 16, v233
	v_max_f32_e32 v3, v174, v174
	v_and_b32_e32 v175, 0xffff0000, v233
	v_max_f32_e32 v3, 0x358637bd, v3
	v_pk_mul_f32 v[134:135], v[170:171], v[134:135]
	v_rcp_f32_e32 v170, v3
	v_max_f32_e32 v3, v175, v175
	v_max_f32_e32 v3, 0x358637bd, v3
	v_rcp_f32_e32 v171, v3
	v_lshlrev_b32_e32 v179, 16, v234
	v_max_f32_e32 v3, v179, v179
	v_and_b32_e32 v180, 0xffff0000, v234
	v_max_f32_e32 v3, 0x358637bd, v3
	v_pk_mul_f32 v[136:137], v[170:171], v[136:137]
	v_rcp_f32_e32 v170, v3
	v_max_f32_e32 v3, v180, v180
	v_max_f32_e32 v3, 0x358637bd, v3
	v_rcp_f32_e32 v171, v3
	v_lshlrev_b32_e32 v181, 16, v235
	v_max_f32_e32 v3, v181, v181
	v_and_b32_e32 v182, 0xffff0000, v235
	v_max_f32_e32 v3, 0x358637bd, v3
	v_pk_mul_f32 v[138:139], v[170:171], v[138:139]
	v_rcp_f32_e32 v170, v3
	v_max_f32_e32 v3, v182, v182
	v_max_f32_e32 v3, 0x358637bd, v3
	v_rcp_f32_e32 v171, v3
	s_nop 0
	v_pk_mul_f32 v[140:141], v[170:171], v[140:141]

; __device__ __forceinline__ float bf_lo(unsigned w) { return __uint_as_float(w << 16); }
; __device__ __forceinline__ float bf_hi(unsigned w) { return __uint_as_float(w & 0xffff0000u); }
;     __device__ __forceinline__ void operator()(f32x4 (&acc)[2][2][4][2], const pg8::Unit& u, int wr, int wc, int fr, int fq) const {
;     ...
;             for (int m = 0; m < 4; ++m) { const size_t row = (size_t)(row0 + ai * 128 + m * 16);
; #pragma unroll
;                 for (int bj = 0; bj < 2; ++bj) { const int col = col0 + bj * 128;
;                     const u32x4 gw = *(const u32x4*)(proj + row * NPROJ + PC_MG + u.sub * D + col);
;                     float g[8] = {bf_lo(gw.x), bf_hi(gw.x), bf_lo(gw.y), bf_hi(gw.y), bf_lo(gw.z), bf_hi(gw.z), bf_lo(gw.w), bf_hi(gw.w)};
;                     if (u.sub < 2) { const u32x4 nw = *(const u32x4*)(proj + row * NPROJ + PC_MG + (u.sub + 1) * D + col);
;                         const float n[8] = {bf_lo(nw.x), bf_hi(nw.x), bf_lo(nw.y), bf_hi(nw.y), bf_lo(nw.z), bf_hi(nw.z), bf_lo(nw.w), bf_hi(nw.w)};
; #pragma unroll
;                         for (int k = 0; k < 8; ++k) g[k] *= __builtin_amdgcn_rcpf(fmaxf(n[k], 1e-6f)); }
;                     f32x4 v0 = acc[ai][bj][m][0], v1 = acc[ai][bj][m][1];
;                     v0[0] *= g[0]; v0[1] *= g[1]; v0[2] *= g[2]; v0[3] *= g[3]; v1[0] *= g[4]; v1[1] *= g[5]; v1[2] *= g[6]; v1[3] *= g[7];
;                     if (u.sub < 2) { acc[ai][bj][m][0] = v0; acc[ai][bj][m][1] = v1; }
.LBB0_1624:
	s_nop 0
	v_or_b32_e32 v134, 48, v168
	v_ashrrev_i32_e32 v135, 31, v134
	v_lshlrev_b64 v[136:137], 15, v[134:135]
	v_lshl_add_u64 v[136:137], s[62:63], 0, v[136:137]
	v_lshl_add_u64 v[170:171], v[136:137], 0, s[52:53]
	v_lshl_add_u64 v[136:137], s[28:29], 1, v[170:171]
	v_lshl_add_u64 v[174:175], v[4:5], 1, v[136:137]
	s_andn2_b64 vcc, exec, s[30:31]
	s_and_b64 vcc, exec, s[14:15]
	v_lshlrev_b32_e32 v172, 16, v220
	v_and_b32_e32 v173, 0xffff0000, v220
	v_lshlrev_b32_e32 v136, 16, v221
	v_and_b32_e32 v137, 0xffff0000, v221
	v_lshlrev_b32_e32 v138, 16, v222
	v_and_b32_e32 v139, 0xffff0000, v222
	v_lshlrev_b32_e32 v140, 16, v223
	v_and_b32_e32 v141, 0xffff0000, v223
	s_cbranch_vccnz .LBB0_1626
	s_add_i32 s30, s28, 0x800
	s_ashr_i32 s31, s30, 31
	v_lshl_add_u64 v[180:181], s[30:31], 1, v[170:171]
	v_lshl_add_u64 v[180:181], v[4:5], 1, v[180:181]
	v_lshlrev_b32_e32 v3, 16, v236
	v_max_f32_e32 v3, v3, v3
	v_and_b32_e32 v169, 0xffff0000, v236
	v_max_f32_e32 v3, 0x358637bd, v3
	v_rcp_f32_e32 v180, v3
	v_max_f32_e32 v3, v169, v169
	v_max_f32_e32 v3, 0x358637bd, v3
	v_lshlrev_b32_e32 v179, 16, v237
	v_and_b32_e32 v184, 0xffff0000, v237
	v_rcp_f32_e32 v181, v3
	v_max_f32_e32 v3, v179, v179
	v_max_f32_e32 v3, 0x358637bd, v3
	v_lshlrev_b32_e32 v185, 16, v238
	v_pk_mul_f32 v[172:173], v[180:181], v[172:173]
	v_rcp_f32_e32 v180, v3
	v_max_f32_e32 v3, v184, v184
	v_max_f32_e32 v3, 0x358637bd, v3
	v_rcp_f32_e32 v181, v3
	v_max_f32_e32 v3, v185, v185
	v_and_b32_e32 v182, 0xffff0000, v238
	v_max_f32_e32 v3, 0x358637bd, v3
	v_pk_mul_f32 v[136:137], v[180:181], v[136:137]
	v_rcp_f32_e32 v180, v3
	v_max_f32_e32 v3, v182, v182
	v_max_f32_e32 v3, 0x358637bd, v3
	v_rcp_f32_e32 v181, v3
	v_lshlrev_b32_e32 v186, 16, v239
	v_max_f32_e32 v3, v186, v186
	v_and_b32_e32 v183, 0xffff0000, v239
	v_max_f32_e32 v3, 0x358637bd, v3
	v_pk_mul_f32 v[138:139], v[180:181], v[138:139]
	v_rcp_f32_e32 v180, v3
	v_max_f32_e32 v3, v183, v183
	v_max_f32_e32 v3, 0x358637bd, v3
	v_rcp_f32_e32 v181, v3
	s_nop 0
	v_pk_mul_f32 v[140:141], v[180:181], v[140:141]

; __device__ __forceinline__ float bf_lo(unsigned w) { return __uint_as_float(w << 16); }
; __device__ __forceinline__ float bf_hi(unsigned w) { return __uint_as_float(w & 0xffff0000u); }
;     __device__ __forceinline__ void operator()(f32x4 (&acc)[2][2][4][2], const pg8::Unit& u, int wr, int wc, int fr, int fq) const {
;     ...
;             for (int m = 0; m < 4; ++m) { const size_t row = (size_t)(row0 + ai * 128 + m * 16);
; #pragma unroll
;                 for (int bj = 0; bj < 2; ++bj) { const int col = col0 + bj * 128;
;                     const u32x4 gw = *(const u32x4*)(proj + row * NPROJ + PC_MG + u.sub * D + col);
;                     float g[8] = {bf_lo(gw.x), bf_hi(gw.x), bf_lo(gw.y), bf_hi(gw.y), bf_lo(gw.z), bf_hi(gw.z), bf_lo(gw.w), bf_hi(gw.w)};
;                     if (u.sub < 2) { const u32x4 nw = *(const u32x4*)(proj + row * NPROJ + PC_MG + (u.sub + 1) * D + col);
;                         const float n[8] = {bf_lo(nw.x), bf_hi(nw.x), bf_lo(nw.y), bf_hi(nw.y), bf_lo(nw.z), bf_hi(nw.z), bf_lo(nw.w), bf_hi(nw.w)};
; #pragma unroll
;                         for (int k = 0; k < 8; ++k) g[k] *= __builtin_amdgcn_rcpf(fmaxf(n[k], 1e-6f)); }
;                     f32x4 v0 = acc[ai][bj][m][0], v1 = acc[ai][bj][m][1];
;                     v0[0] *= g[0]; v0[1] *= g[1]; v0[2] *= g[2]; v0[3] *= g[3]; v1[0] *= g[4]; v1[1] *= g[5]; v1[2] *= g[6]; v1[3] *= g[7];
;                     if (u.sub < 2) { acc[ai][bj][m][0] = v0; acc[ai][bj][m][1] = v1; }
.LBB0_1634:
	s_nop 0
	v_add_u32_e32 v134, 0x80, v168
	v_ashrrev_i32_e32 v135, 31, v134
	v_lshlrev_b64 v[136:137], 15, v[134:135]
	v_lshl_add_u64 v[136:137], s[62:63], 0, v[136:137]
	v_lshl_add_u64 v[170:171], v[136:137], 0, s[52:53]
	v_lshl_add_u64 v[136:137], s[28:29], 1, v[170:171]
	v_lshl_add_u64 v[174:175], v[4:5], 1, v[136:137]
	s_mov_b32 s101, 0
	s_mov_b32 s100, 0x400000
	v_lshl_add_u64 v[244:245], v[246:247], 0, s[100:101]
	global_load_dwordx4 v[212:215], v[244:245], off
	global_load_dwordx4 v[216:219], v[244:245], off offset:256
	s_mov_b32 s100, 0x401000
	v_lshl_add_u64 v[244:245], v[246:247], 0, s[100:101]
	global_load_dwordx4 v[228:231], v[244:245], off
	global_load_dwordx4 v[232:235], v[244:245], off offset:256
	s_mov_b32 s100, 0x480000
	v_lshl_add_u64 v[244:245], v[246:247], 0, s[100:101]
	global_load_dwordx4 v[220:223], v[244:245], off
	global_load_dwordx4 v[224:227], v[244:245], off offset:256
	s_mov_b32 s100, 0x481000
	v_lshl_add_u64 v[244:245], v[246:247], 0, s[100:101]
	global_load_dwordx4 v[236:239], v[244:245], off
	global_load_dwordx4 v[240:243], v[244:245], off offset:256
	s_waitcnt vmcnt(0)
	s_andn2_b64 vcc, exec, s[30:31]
	s_and_b64 vcc, exec, s[14:15]
	v_lshlrev_b32_e32 v172, 16, v212
	v_and_b32_e32 v173, 0xffff0000, v212
	v_lshlrev_b32_e32 v136, 16, v213
	v_and_b32_e32 v137, 0xffff0000, v213
	v_lshlrev_b32_e32 v138, 16, v214
	v_and_b32_e32 v139, 0xffff0000, v214
	v_lshlrev_b32_e32 v140, 16, v215
	v_and_b32_e32 v141, 0xffff0000, v215
	s_cbranch_vccnz .LBB0_1636
	s_add_i32 s30, s28, 0x800
	s_ashr_i32 s31, s30, 31
	v_lshl_add_u64 v[180:181], s[30:31], 1, v[170:171]
	v_lshl_add_u64 v[180:181], v[4:5], 1, v[180:181]
	v_lshlrev_b32_e32 v3, 16, v228
	v_max_f32_e32 v3, v3, v3
	v_and_b32_e32 v169, 0xffff0000, v228
	v_max_f32_e32 v3, 0x358637bd, v3
	v_rcp_f32_e32 v180, v3
	v_max_f32_e32 v3, v169, v169
	v_max_f32_e32 v3, 0x358637bd, v3
	v_lshlrev_b32_e32 v179, 16, v229
	v_and_b32_e32 v184, 0xffff0000, v229
	v_rcp_f32_e32 v181, v3
	v_max_f32_e32 v3, v179, v179
	v_max_f32_e32 v3, 0x358637bd, v3
	v_lshlrev_b32_e32 v185, 16, v230
	v_pk_mul_f32 v[172:173], v[180:181], v[172:173]
	v_rcp_f32_e32 v180, v3
	v_max_f32_e32 v3, v184, v184
	v_max_f32_e32 v3, 0x358637bd, v3
	v_rcp_f32_e32 v181, v3
	v_max_f32_e32 v3, v185, v185
	v_and_b32_e32 v182, 0xffff0000, v230
	v_max_f32_e32 v3, 0x358637bd, v3
	v_pk_mul_f32 v[136:137], v[180:181], v[136:137]
	v_rcp_f32_e32 v180, v3
	v_max_f32_e32 v3, v182, v182
	v_max_f32_e32 v3, 0x358637bd, v3
	v_rcp_f32_e32 v181, v3
	v_lshlrev_b32_e32 v186, 16, v231
	v_max_f32_e32 v3, v186, v186
	v_and_b32_e32 v183, 0xffff0000, v231
	v_max_f32_e32 v3, 0x358637bd, v3
	v_pk_mul_f32 v[138:139], v[180:181], v[138:139]
	v_rcp_f32_e32 v180, v3
	v_max_f32_e32 v3, v183, v183
	v_max_f32_e32 v3, 0x358637bd, v3
	v_rcp_f32_e32 v181, v3
	s_nop 0
	v_pk_mul_f32 v[140:141], v[180:181], v[140:141]

; __device__ __forceinline__ float bf_lo(unsigned w) { return __uint_as_float(w << 16); }
; __device__ __forceinline__ float bf_hi(unsigned w) { return __uint_as_float(w & 0xffff0000u); }
;     __device__ __forceinline__ void operator()(f32x4 (&acc)[2][2][4][2], const pg8::Unit& u, int wr, int wc, int fr, int fq) const {
;     ...
;             for (int m = 0; m < 4; ++m) { const size_t row = (size_t)(row0 + ai * 128 + m * 16);
; #pragma unroll
;                 for (int bj = 0; bj < 2; ++bj) { const int col = col0 + bj * 128;
;                     const u32x4 gw = *(const u32x4*)(proj + row * NPROJ + PC_MG + u.sub * D + col);
;                     float g[8] = {bf_lo(gw.x), bf_hi(gw.x), bf_lo(gw.y), bf_hi(gw.y), bf_lo(gw.z), bf_hi(gw.z), bf_lo(gw.w), bf_hi(gw.w)};
;                     if (u.sub < 2) { const u32x4 nw = *(const u32x4*)(proj + row * NPROJ + PC_MG + (u.sub + 1) * D + col);
;                         const float n[8] = {bf_lo(nw.x), bf_hi(nw.x), bf_lo(nw.y), bf_hi(nw.y), bf_lo(nw.z), bf_hi(nw.z), bf_lo(nw.w), bf_hi(nw.w)};
; #pragma unroll
;                         for (int k = 0; k < 8; ++k) g[k] *= __builtin_amdgcn_rcpf(fmaxf(n[k], 1e-6f)); }
;                     f32x4 v0 = acc[ai][bj][m][0], v1 = acc[ai][bj][m][1];
;                     v0[0] *= g[0]; v0[1] *= g[1]; v0[2] *= g[2]; v0[3] *= g[3]; v1[0] *= g[4]; v1[1] *= g[5]; v1[2] *= g[6]; v1[3] *= g[7];
;                     if (u.sub < 2) { acc[ai][bj][m][0] = v0; acc[ai][bj][m][1] = v1; }
.LBB0_1644:
	s_nop 0
	v_add_u32_e32 v134, 0x90, v168
	v_ashrrev_i32_e32 v135, 31, v134
	v_lshlrev_b64 v[136:137], 15, v[134:135]
	v_lshl_add_u64 v[136:137], s[62:63], 0, v[136:137]
	v_lshl_add_u64 v[170:171], v[136:137], 0, s[52:53]
	v_lshl_add_u64 v[136:137], s[28:29], 1, v[170:171]
	v_lshl_add_u64 v[174:175], v[4:5], 1, v[136:137]
	s_andn2_b64 vcc, exec, s[30:31]
	s_and_b64 vcc, exec, s[14:15]
	v_lshlrev_b32_e32 v172, 16, v220
	v_and_b32_e32 v173, 0xffff0000, v220
	v_lshlrev_b32_e32 v136, 16, v221
	v_and_b32_e32 v137, 0xffff0000, v221
	v_lshlrev_b32_e32 v138, 16, v222
	v_and_b32_e32 v139, 0xffff0000, v222
	v_lshlrev_b32_e32 v140, 16, v223
	v_and_b32_e32 v141, 0xffff0000, v223
	s_cbranch_vccnz .LBB0_1646
	s_add_i32 s30, s28, 0x800
	s_ashr_i32 s31, s30, 31
	v_lshl_add_u64 v[180:181], s[30:31], 1, v[170:171]
	v_lshl_add_u64 v[180:181], v[4:5], 1, v[180:181]
	v_lshlrev_b32_e32 v3, 16, v236
	v_max_f32_e32 v3, v3, v3
	v_and_b32_e32 v169, 0xffff0000, v236
	v_max_f32_e32 v3, 0x358637bd, v3
	v_rcp_f32_e32 v180, v3
	v_max_f32_e32 v3, v169, v169
	v_max_f32_e32 v3, 0x358637bd, v3
	v_lshlrev_b32_e32 v179, 16, v237
	v_and_b32_e32 v184, 0xffff0000, v237
	v_rcp_f32_e32 v181, v3
	v_max_f32_e32 v3, v179, v179
	v_max_f32_e32 v3, 0x358637bd, v3
	v_lshlrev_b32_e32 v185, 16, v238
	v_pk_mul_f32 v[172:173], v[180:181], v[172:173]
	v_rcp_f32_e32 v180, v3
	v_max_f32_e32 v3, v184, v184
	v_max_f32_e32 v3, 0x358637bd, v3
	v_rcp_f32_e32 v181, v3
	v_max_f32_e32 v3, v185, v185
	v_and_b32_e32 v182, 0xffff0000, v238
	v_max_f32_e32 v3, 0x358637bd, v3
	v_pk_mul_f32 v[136:137], v[180:181], v[136:137]
	v_rcp_f32_e32 v180, v3
	v_max_f32_e32 v3, v182, v182
	v_max_f32_e32 v3, 0x358637bd, v3
	v_rcp_f32_e32 v181, v3
	v_lshlrev_b32_e32 v186, 16, v239
	v_max_f32_e32 v3, v186, v186
	v_and_b32_e32 v183, 0xffff0000, v239
	v_max_f32_e32 v3, 0x358637bd, v3
	v_pk_mul_f32 v[138:139], v[180:181], v[138:139]
	v_rcp_f32_e32 v180, v3
	v_max_f32_e32 v3, v183, v183
	v_max_f32_e32 v3, 0x358637bd, v3
	v_rcp_f32_e32 v181, v3
	s_nop 0
	v_pk_mul_f32 v[140:141], v[180:181], v[140:141]

; __device__ __forceinline__ float bf_lo(unsigned w) { return __uint_as_float(w << 16); }
; __device__ __forceinline__ float bf_hi(unsigned w) { return __uint_as_float(w & 0xffff0000u); }
;     __device__ __forceinline__ void operator()(f32x4 (&acc)[2][2][4][2], const pg8::Unit& u, int wr, int wc, int fr, int fq) const {
;     ...
;             for (int m = 0; m < 4; ++m) { const size_t row = (size_t)(row0 + ai * 128 + m * 16);
; #pragma unroll
;                 for (int bj = 0; bj < 2; ++bj) { const int col = col0 + bj * 128;
;                     const u32x4 gw = *(const u32x4*)(proj + row * NPROJ + PC_MG + u.sub * D + col);
;                     float g[8] = {bf_lo(gw.x), bf_hi(gw.x), bf_lo(gw.y), bf_hi(gw.y), bf_lo(gw.z), bf_hi(gw.z), bf_lo(gw.w), bf_hi(gw.w)};
;                     if (u.sub < 2) { const u32x4 nw = *(const u32x4*)(proj + row * NPROJ + PC_MG + (u.sub + 1) * D + col);
;                         const float n[8] = {bf_lo(nw.x), bf_hi(nw.x), bf_lo(nw.y), bf_hi(nw.y), bf_lo(nw.z), bf_hi(nw.z), bf_lo(nw.w), bf_hi(nw.w)};
; #pragma unroll
;                         for (int k = 0; k < 8; ++k) g[k] *= __builtin_amdgcn_rcpf(fmaxf(n[k], 1e-6f)); }
;                     f32x4 v0 = acc[ai][bj][m][0], v1 = acc[ai][bj][m][1];
;                     v0[0] *= g[0]; v0[1] *= g[1]; v0[2] *= g[2]; v0[3] *= g[3]; v1[0] *= g[4]; v1[1] *= g[5]; v1[2] *= g[6]; v1[3] *= g[7];
;                     if (u.sub < 2) { acc[ai][bj][m][0] = v0; acc[ai][bj][m][1] = v1; }
.LBB0_1654:
	s_nop 0
	v_add_u32_e32 v134, 0xa0, v168
	v_ashrrev_i32_e32 v135, 31, v134
	v_lshlrev_b64 v[136:137], 15, v[134:135]
	v_lshl_add_u64 v[136:137], s[62:63], 0, v[136:137]
	v_lshl_add_u64 v[170:171], v[136:137], 0, s[52:53]
	v_lshl_add_u64 v[136:137], s[28:29], 1, v[170:171]
	v_lshl_add_u64 v[174:175], v[4:5], 1, v[136:137]
	s_mov_b32 s101, 0
	s_mov_b32 s100, 0x500000
	v_lshl_add_u64 v[244:245], v[246:247], 0, s[100:101]
	global_load_dwordx4 v[212:215], v[244:245], off
	global_load_dwordx4 v[216:219], v[244:245], off offset:256
	s_mov_b32 s100, 0x501000
	v_lshl_add_u64 v[244:245], v[246:247], 0, s[100:101]
	global_load_dwordx4 v[228:231], v[244:245], off
	global_load_dwordx4 v[232:235], v[244:245], off offset:256
	s_mov_b32 s100, 0x580000
	v_lshl_add_u64 v[244:245], v[246:247], 0, s[100:101]
	global_load_dwordx4 v[220:223], v[244:245], off
	global_load_dwordx4 v[224:227], v[244:245], off offset:256
	s_mov_b32 s100, 0x581000
	v_lshl_add_u64 v[244:245], v[246:247], 0, s[100:101]
	global_load_dwordx4 v[236:239], v[244:245], off
	global_load_dwordx4 v[240:243], v[244:245], off offset:256
	s_waitcnt vmcnt(0)
	s_andn2_b64 vcc, exec, s[30:31]
	s_and_b64 vcc, exec, s[14:15]
	v_lshlrev_b32_e32 v172, 16, v212
	v_and_b32_e32 v173, 0xffff0000, v212
	v_lshlrev_b32_e32 v136, 16, v213
	v_and_b32_e32 v137, 0xffff0000, v213
	v_lshlrev_b32_e32 v138, 16, v214
	v_and_b32_e32 v139, 0xffff0000, v214
	v_lshlrev_b32_e32 v140, 16, v215
	v_and_b32_e32 v141, 0xffff0000, v215
	s_cbranch_vccnz .LBB0_1656
	s_add_i32 s30, s28, 0x800
	s_ashr_i32 s31, s30, 31
	v_lshl_add_u64 v[180:181], s[30:31], 1, v[170:171]
	v_lshl_add_u64 v[180:181], v[4:5], 1, v[180:181]
	v_lshlrev_b32_e32 v3, 16, v228
	v_max_f32_e32 v3, v3, v3
	v_and_b32_e32 v169, 0xffff0000, v228
	v_max_f32_e32 v3, 0x358637bd, v3
	v_rcp_f32_e32 v180, v3
	v_max_f32_e32 v3, v169, v169
	v_max_f32_e32 v3, 0x358637bd, v3
	v_lshlrev_b32_e32 v179, 16, v229
	v_and_b32_e32 v184, 0xffff0000, v229
	v_rcp_f32_e32 v181, v3
	v_max_f32_e32 v3, v179, v179
	v_max_f32_e32 v3, 0x358637bd, v3
	v_lshlrev_b32_e32 v185, 16, v230
	v_pk_mul_f32 v[172:173], v[180:181], v[172:173]
	v_rcp_f32_e32 v180, v3
	v_max_f32_e32 v3, v184, v184
	v_max_f32_e32 v3, 0x358637bd, v3
	v_rcp_f32_e32 v181, v3
	v_max_f32_e32 v3, v185, v185
	v_and_b32_e32 v182, 0xffff0000, v230
	v_max_f32_e32 v3, 0x358637bd, v3
	v_pk_mul_f32 v[136:137], v[180:181], v[136:137]
	v_rcp_f32_e32 v180, v3
	v_max_f32_e32 v3, v182, v182
	v_max_f32_e32 v3, 0x358637bd, v3
	v_rcp_f32_e32 v181, v3
	v_lshlrev_b32_e32 v186, 16, v231
	v_max_f32_e32 v3, v186, v186
	v_and_b32_e32 v183, 0xffff0000, v231
	v_max_f32_e32 v3, 0x358637bd, v3
	v_pk_mul_f32 v[138:139], v[180:181], v[138:139]
	v_rcp_f32_e32 v180, v3
	v_max_f32_e32 v3, v183, v183
	v_max_f32_e32 v3, 0x358637bd, v3
	v_rcp_f32_e32 v181, v3
	s_nop 0
	v_pk_mul_f32 v[140:141], v[180:181], v[140:141]

; __device__ __forceinline__ float bf_lo(unsigned w) { return __uint_as_float(w << 16); }
; __device__ __forceinline__ float bf_hi(unsigned w) { return __uint_as_float(w & 0xffff0000u); }
;     __device__ __forceinline__ void operator()(f32x4 (&acc)[2][2][4][2], const pg8::Unit& u, int wr, int wc, int fr, int fq) const {
;     ...
;             for (int m = 0; m < 4; ++m) { const size_t row = (size_t)(row0 + ai * 128 + m * 16);
; #pragma unroll
;                 for (int bj = 0; bj < 2; ++bj) { const int col = col0 + bj * 128;
;                     const u32x4 gw = *(const u32x4*)(proj + row * NPROJ + PC_MG + u.sub * D + col);
;                     float g[8] = {bf_lo(gw.x), bf_hi(gw.x), bf_lo(gw.y), bf_hi(gw.y), bf_lo(gw.z), bf_hi(gw.z), bf_lo(gw.w), bf_hi(gw.w)};
;                     if (u.sub < 2) { const u32x4 nw = *(const u32x4*)(proj + row * NPROJ + PC_MG + (u.sub + 1) * D + col);
;                         const float n[8] = {bf_lo(nw.x), bf_hi(nw.x), bf_lo(nw.y), bf_hi(nw.y), bf_lo(nw.z), bf_hi(nw.z), bf_lo(nw.w), bf_hi(nw.w)};
; #pragma unroll
;                         for (int k = 0; k < 8; ++k) g[k] *= __builtin_amdgcn_rcpf(fmaxf(n[k], 1e-6f)); }
;                     f32x4 v0 = acc[ai][bj][m][0], v1 = acc[ai][bj][m][1];
;                     v0[0] *= g[0]; v0[1] *= g[1]; v0[2] *= g[2]; v0[3] *= g[3]; v1[0] *= g[4]; v1[1] *= g[5]; v1[2] *= g[6]; v1[3] *= g[7];
;                     if (u.sub < 2) { acc[ai][bj][m][0] = v0; acc[ai][bj][m][1] = v1; }
.LBB0_1664:
	s_nop 0
	v_add_u32_e32 v134, 0xb0, v168
	v_ashrrev_i32_e32 v135, 31, v134
	v_lshlrev_b64 v[136:137], 15, v[134:135]
	v_lshl_add_u64 v[136:137], s[62:63], 0, v[136:137]
	v_lshl_add_u64 v[168:169], v[136:137], 0, s[52:53]
	v_lshl_add_u64 v[136:137], s[28:29], 1, v[168:169]
	v_lshl_add_u64 v[172:173], v[4:5], 1, v[136:137]
	s_andn2_b64 vcc, exec, s[30:31]
	s_and_b64 vcc, exec, s[14:15]
	v_lshlrev_b32_e32 v170, 16, v220
	v_and_b32_e32 v171, 0xffff0000, v220
	v_lshlrev_b32_e32 v136, 16, v221
	v_and_b32_e32 v137, 0xffff0000, v221
	v_lshlrev_b32_e32 v138, 16, v222
	v_and_b32_e32 v139, 0xffff0000, v222
	v_lshlrev_b32_e32 v140, 16, v223
	v_and_b32_e32 v141, 0xffff0000, v223
	s_cbranch_vccnz .LBB0_1666
	s_add_i32 s30, s28, 0x800
	s_ashr_i32 s31, s30, 31
	v_lshl_add_u64 v[174:175], s[30:31], 1, v[168:169]
	v_lshl_add_u64 v[174:175], v[4:5], 1, v[174:175]
	v_lshlrev_b32_e32 v3, 16, v236
	v_max_f32_e32 v3, v3, v3
	v_and_b32_e32 v175, 0xffff0000, v236
	v_max_f32_e32 v3, 0x358637bd, v3
	v_rcp_f32_e32 v174, v3
	v_max_f32_e32 v3, v175, v175
	v_max_f32_e32 v3, 0x358637bd, v3
	v_rcp_f32_e32 v175, v3
	v_lshlrev_b32_e32 v179, 16, v237
	v_max_f32_e32 v3, v179, v179
	v_and_b32_e32 v180, 0xffff0000, v237
	v_max_f32_e32 v3, 0x358637bd, v3
	v_pk_mul_f32 v[170:171], v[174:175], v[170:171]
	v_rcp_f32_e32 v174, v3
	v_max_f32_e32 v3, v180, v180
	v_max_f32_e32 v3, 0x358637bd, v3
	v_rcp_f32_e32 v175, v3
	v_lshlrev_b32_e32 v181, 16, v238
	v_max_f32_e32 v3, v181, v181
	v_and_b32_e32 v182, 0xffff0000, v238
	v_max_f32_e32 v3, 0x358637bd, v3
	v_pk_mul_f32 v[136:137], v[174:175], v[136:137]
	v_rcp_f32_e32 v174, v3
	v_max_f32_e32 v3, v182, v182
	v_max_f32_e32 v3, 0x358637bd, v3
	v_rcp_f32_e32 v175, v3
	v_lshlrev_b32_e32 v184, 16, v239
	v_max_f32_e32 v3, v184, v184
	v_and_b32_e32 v183, 0xffff0000, v239
	v_max_f32_e32 v3, 0x358637bd, v3
	v_pk_mul_f32 v[138:139], v[174:175], v[138:139]
	v_rcp_f32_e32 v174, v3
	v_max_f32_e32 v3, v183, v183
	v_max_f32_e32 v3, 0x358637bd, v3
	v_rcp_f32_e32 v175, v3
	s_nop 0
	v_pk_mul_f32 v[140:141], v[174:175], v[140:141]

; __device__ __forceinline__ float bf_lo(unsigned w) { return __uint_as_float(w << 16); }
; __device__ __forceinline__ float bf_hi(unsigned w) { return __uint_as_float(w & 0xffff0000u); }
;     __device__ __forceinline__ void operator()(f32x4 (&acc)[2][2][4][2], const pg8::Unit& u, int wr, int wc, int fr, int fq) const {
;     ...
;             for (int m = 0; m < 4; ++m) { const size_t row = (size_t)(row0 + ai * 128 + m * 16);
; #pragma unroll
;                 for (int bj = 0; bj < 2; ++bj) { const int col = col0 + bj * 128;
;                     const u32x4 gw = *(const u32x4*)(proj + row * NPROJ + PC_MG + u.sub * D + col);
;                     float g[8] = {bf_lo(gw.x), bf_hi(gw.x), bf_lo(gw.y), bf_hi(gw.y), bf_lo(gw.z), bf_hi(gw.z), bf_lo(gw.w), bf_hi(gw.w)};
;                     if (u.sub < 2) { const u32x4 nw = *(const u32x4*)(proj + row * NPROJ + PC_MG + (u.sub + 1) * D + col);
;                         const float n[8] = {bf_lo(nw.x), bf_hi(nw.x), bf_lo(nw.y), bf_hi(nw.y), bf_lo(nw.z), bf_hi(nw.z), bf_lo(nw.w), bf_hi(nw.w)};
; #pragma unroll
;                         for (int k = 0; k < 8; ++k) g[k] *= __builtin_amdgcn_rcpf(fmaxf(n[k], 1e-6f)); }
;                     f32x4 v0 = acc[ai][bj][m][0], v1 = acc[ai][bj][m][1];
;                     v0[0] *= g[0]; v0[1] *= g[1]; v0[2] *= g[2]; v0[3] *= g[3]; v1[0] *= g[4]; v1[1] *= g[5]; v1[2] *= g[6]; v1[3] *= g[7];
;                     if (u.sub < 2) { acc[ai][bj][m][0] = v0; acc[ai][bj][m][1] = v1; }
.LBB0_1669:
	s_andn2_b64 vcc, exec, s[30:31]
	s_and_b64 vcc, exec, s[14:15]
	v_lshlrev_b32_e32 v134, 16, v224
	v_and_b32_e32 v135, 0xffff0000, v224
	v_lshlrev_b32_e32 v136, 16, v225
	v_and_b32_e32 v137, 0xffff0000, v225
	v_lshlrev_b32_e32 v138, 16, v226
	v_and_b32_e32 v139, 0xffff0000, v226
	v_lshlrev_b32_e32 v140, 16, v227
	v_and_b32_e32 v141, 0xffff0000, v227
	s_cbranch_vccnz .LBB0_1671
	s_add_i32 s14, s28, 0x800
	s_ashr_i32 s15, s14, 31
	v_lshl_add_u64 v[168:169], s[14:15], 1, v[168:169]
	v_lshl_add_u64 v[4:5], v[4:5], 1, v[168:169]
	v_lshlrev_b32_e32 v3, 16, v240
	v_max_f32_e32 v3, v3, v3
	v_and_b32_e32 v5, 0xffff0000, v240
	v_max_f32_e32 v3, 0x358637bd, v3
	v_rcp_f32_e32 v4, v3
	v_max_f32_e32 v3, v5, v5
	v_max_f32_e32 v3, 0x358637bd, v3
	v_rcp_f32_e32 v5, v3
	v_lshlrev_b32_e32 v168, 16, v241
	v_max_f32_e32 v3, v168, v168
	v_and_b32_e32 v169, 0xffff0000, v241
	v_max_f32_e32 v3, 0x358637bd, v3
	v_pk_mul_f32 v[134:135], v[4:5], v[134:135]
	v_rcp_f32_e32 v4, v3
	v_max_f32_e32 v3, v169, v169
	v_max_f32_e32 v3, 0x358637bd, v3
	v_rcp_f32_e32 v5, v3
	v_lshlrev_b32_e32 v172, 16, v242
	v_max_f32_e32 v3, v172, v172
	v_and_b32_e32 v173, 0xffff0000, v242
	v_max_f32_e32 v3, 0x358637bd, v3
	v_pk_mul_f32 v[136:137], v[4:5], v[136:137]
	v_rcp_f32_e32 v4, v3
	v_max_f32_e32 v3, v173, v173
	v_max_f32_e32 v3, 0x358637bd, v3
	v_rcp_f32_e32 v5, v3
	v_lshlrev_b32_e32 v174, 16, v243
	v_max_f32_e32 v3, v174, v174
	v_and_b32_e32 v175, 0xffff0000, v243
	v_max_f32_e32 v3, 0x358637bd, v3
	v_pk_mul_f32 v[138:139], v[4:5], v[138:139]
	v_rcp_f32_e32 v4, v3
	v_max_f32_e32 v3, v175, v175
	v_max_f32_e32 v3, 0x358637bd, v3
	v_rcp_f32_e32 v5, v3
	s_nop 0
	v_pk_mul_f32 v[140:141], v[4:5], v[140:141]
